# G1 items dealt per XCD (rows produced through the same L2) + seam ph5->6 XCD-local (4 local seams now)
# speedup vs baseline: 1.0164x; 1.0020x over previous
; __device__ __forceinline__ unsigned xb_add(unsigned* p, unsigned v) { return __hip_atomic_fetch_add(p, v, __ATOMIC_RELAXED, __HIP_MEMORY_SCOPE_AGENT); }
; __device__ __forceinline__ void xcd_barrier(const XcdBarrier& b) {
;     asm volatile("s_waitcnt vmcnt(0)" ::: "memory");
;     __syncthreads();
;     if (threadIdx.x == 0) {
;         unsigned* bar = b.bar;
;         __builtin_amdgcn_s_waitcnt(0);
;         unsigned nloc = b.st[0], nx = b.st[1];
;         if (nloc == 0u) { xcd_barrier_complete(bar, b.x, nloc, nx); b.st[0] = nloc; b.st[1] = nx; }
;         const unsigned old = xb_add(&bar[XB_XSUB(b.x)], 1u);
;         const unsigned gen = old / nloc;
;         if (old + 1u == (gen + 1u) * nloc) {
.LBB0_1904:
	s_cmp_lt_i32 s57, 7
	s_cbranch_scc1 .LBB0_1958
	s_waitcnt vmcnt(0)
	s_waitcnt lgkmcnt(0)
	s_barrier
	s_and_saveexec_b64 s[6:7], s[4:5]
	s_cbranch_execz .LBB0_1957
	v_mov_b32_e32 v0, 0
	global_load_dwordx4 v[6:9], v0, s[50:51] offset:256 sc1
	global_load_dwordx4 v[10:13], v0, s[50:51] offset:272 sc1
	s_lshl_b32 s3, s33, 8
	s_add_u32 s8, s50, s3
	s_addc_u32 s9, s51, 0
	v_mov_b32_e32 v3, 0x2000
	global_load_dword v4, v3, s[8:9] offset:1024 sc1
	v_mov_b32_e32 v2, 0x20000
	ds_read_b32 v2, v2
	s_waitcnt vmcnt(0) lgkmcnt(0)
	v_add_u32_e32 v14, -1, v6
	v_and_b32_e32 v1, v14, v6
	v_min_u32_e32 v15, v6, v7
	v_add_u32_e32 v14, -1, v7
	v_and_or_b32 v1, v14, v7, v1
	v_min_u32_e32 v15, v15, v8
	v_add_u32_e32 v14, -1, v8
	v_and_or_b32 v1, v14, v8, v1
	v_min_u32_e32 v15, v15, v9
	v_add_u32_e32 v14, -1, v9
	v_and_or_b32 v1, v14, v9, v1
	v_min_u32_e32 v15, v15, v10
	v_add_u32_e32 v14, -1, v10
	v_and_or_b32 v1, v14, v10, v1
	v_min_u32_e32 v15, v15, v11
	v_add_u32_e32 v14, -1, v11
	v_and_or_b32 v1, v14, v11, v1
	v_min_u32_e32 v15, v15, v12
	v_add_u32_e32 v14, -1, v12
	v_and_or_b32 v1, v14, v12, v1
	v_min_u32_e32 v15, v15, v13
	v_add_u32_e32 v14, -1, v13
	v_and_or_b32 v1, v14, v13, v1
	s_nop 0
	v_readfirstlane_b32 s10, v1
	v_readfirstlane_b32 s13, v15
	v_readfirstlane_b32 s11, v4
	v_readfirstlane_b32 s12, v2
	s_nop 1
	s_cmp_lg_u32 s10, 0
	s_cbranch_scc1 .Lseam56_full
	s_cmp_eq_u32 s13, 0
	s_cbranch_scc1 .Lseam56_full
	s_cmpk_lg_i32 s58, 0x100
	s_cbranch_scc1 .Lseam56_full
	s_cmp_eq_u32 s12, 0
	s_cbranch_scc1 .Lseam56_full
	v_mov_b32_e32 v3, 0x1000
	v_mov_b32_e32 v5, 1
	global_atomic_add v3, v3, v5, s[8:9] offset:1024 sc0
	s_waitcnt vmcnt(0)
	v_readfirstlane_b32 s13, v3
	s_add_i32 s14, s11, 1
	s_mul_i32 s14, s14, s12
	s_add_i32 s13, s13, 1
	v_mov_b32_e32 v3, 0x2000
	s_cmp_eq_u32 s13, s14
	s_cbranch_scc1 .Lseam56_lead

; __device__ __forceinline__ Item decode_item(int it) { Item I; if (it < 1024) { const int b = it >> 8; I.h = (it >> 6) & 3; I.row0 = b * SEQ + (it & 63) * 64; I.L = 64; } else { const int j = it - 1024; I.h = j & 3; I.row0 = MP_ROWS + (j >> 2) * 16; I.L = 16; } I.j = it; return I; }
; __device__ __forceinline__ void gla_g1(const Params& P, unsigned char* lds) {
;     const int tid = threadIdx.x, wid = tid >> 6, lane = tid & 63, fr = lane & 15, fq = lane >> 4;
;     const bf16_t* kg = (const bf16_t*)(P.ws + O_K); const bf16_t* vT = (const bf16_t*)(P.ws + O_VT);
;     bf16_t* KVT = (bf16_t*)(P.ws + O_KVT); float* dec = (float*)(P.ws + O_DEC);
;     const float* bsh = (const float*)(lds + L_BSH); bf16_t* kT = (bf16_t*)(lds + L_KT);
;     for (int it = blockIdx.x; it < NITEM; it += gridDim.x) {
;         const Item I = decode_item(it);
.LBB0_1958:
	s_cmp_lt_i32 s56, 7
	s_cselect_b64 s[6:7], -1, 0
	s_cmp_gt_i32 s57, 6
	s_cselect_b64 s[8:9], -1, 0
	s_and_b64 s[6:7], s[6:7], s[8:9]
	s_andn2_b64 vcc, exec, s[6:7]
	s_cbranch_vccnz .LBB0_2073
	s_mov_b64 s[6:7], s[50:51]
	v_writelane_b32 v240, s6, 2
	s_mov_b64 s[50:51], s[94:95]
	s_cmpk_gt_i32 s2, 0x43f
	v_writelane_b32 v240, s7, 3
	v_writelane_b32 v240, s4, 4
	s_nop 1
	v_writelane_b32 v240, s5, 5
	s_mov_b32 s4, s96
	s_cbranch_scc1 .LBB0_1978
	s_waitcnt lgkmcnt(0)
	s_load_dwordx2 s[16:17], s[0:1], 0xc0
	s_load_dwordx4 s[60:63], s[0:1], 0x70
	v_and_b32_e32 v94, 0x7f, v210
	v_lshrrev_b32_e32 v1, 7, v210
	v_lshlrev_b32_e32 v0, 2, v210
	v_lshl_add_u32 v112, v94, 2, 0
	v_lshlrev_b32_e32 v2, 13, v1
	v_add_u32_e32 v113, v112, v2
	v_or_b32_e32 v2, 0x7e00, v0
	v_lshlrev_b32_e32 v64, 1, v94
	v_mov_b32_e32 v65, 0
	v_add_u32_e32 v114, 0, v2
	s_waitcnt lgkmcnt(0)
	v_lshl_add_u64 v[2:3], s[16:17], 0, v[64:65]
	s_mov_b64 s[18:19], 0x614dc00
	v_lshlrev_b32_e32 v95, 4, v1
	v_lshlrev_b32_e32 v7, 10, v1
	v_lshl_add_u64 v[66:67], v[2:3], 0, s[18:19]
	v_mul_u32_u24_e32 v2, 0x8c, v94
	v_lshlrev_b32_e32 v1, 5, v1
	v_add3_u32 v115, v112, v2, v1
	v_mov_b32_e32 v1, v65
	v_bfe_u32 v5, v210, 4, 2
	v_add_u32_e32 v111, 0, v0
	v_lshl_add_u64 v[0:1], s[16:17], 0, v[0:1]
	s_mov_b64 s[18:19], 0x2ffdc00
	v_and_b32_e32 v4, 15, v210
	v_lshl_add_u64 v[68:69], v[0:1], 0, s[18:19]
	v_lshlrev_b32_e32 v70, 3, v5
	v_lshrrev_b32_e32 v0, 1, v210
	s_movk_i32 s18, 0x1e0
	v_mov_b32_e32 v71, v65
	v_and_or_b32 v116, v0, s18, v4
	v_lshl_add_u64 v[0:1], s[16:17], 0, v[70:71]
	s_mov_b64 s[18:19], 0xbacdc00
	v_lshl_add_u64 v[72:73], v[0:1], 0, s[18:19]
	s_mov_b64 s[18:19], 0xbacdc20
	v_lshl_add_u64 v[74:75], v[0:1], 0, s[18:19]
	s_mov_b64 s[18:19], 0xbacdc40
	v_lshl_add_u64 v[76:77], v[0:1], 0, s[18:19]
	s_mov_b64 s[18:19], 0xbacdc60
	v_lshl_add_u64 v[78:79], v[0:1], 0, s[18:19]
	s_mov_b64 s[18:19], 0xbacdc80
	v_lshl_add_u64 v[80:81], v[0:1], 0, s[18:19]
	s_mov_b64 s[18:19], 0xbacdca0
	v_lshlrev_b32_e32 v6, 4, v210
	v_lshl_add_u64 v[82:83], v[0:1], 0, s[18:19]
	s_mov_b64 s[18:19], 0xbacdcc0
	s_add_u32 s3, s16, 0x9a2dc00
	v_or_b32_e32 v96, 1, v95
	v_or_b32_e32 v97, 2, v95
	v_or_b32_e32 v98, 3, v95
	v_or_b32_e32 v99, 4, v95
	v_or_b32_e32 v100, 5, v95
	v_or_b32_e32 v101, 6, v95
	v_or_b32_e32 v102, 7, v95
	v_or_b32_e32 v103, 8, v95
	v_or_b32_e32 v104, 9, v95
	v_or_b32_e32 v105, 10, v95
	v_or_b32_e32 v106, 11, v95
	v_or_b32_e32 v107, 12, v95
	v_or_b32_e32 v108, 13, v95
	v_or_b32_e32 v109, 14, v95
	v_or_b32_e32 v110, 15, v95
	v_lshl_add_u64 v[84:85], v[0:1], 0, s[18:19]
	s_mov_b64 s[18:19], 0xbacdce0
	v_and_b32_e32 v64, 48, v6
	s_movk_i32 s6, 0x100
	s_addc_u32 s85, s17, 0
	s_movk_i32 s10, 0x7f
	v_lshlrev_b32_e32 v8, 6, v96
	v_lshlrev_b32_e32 v9, 6, v97
	v_lshlrev_b32_e32 v10, 6, v98
	v_lshlrev_b32_e32 v11, 6, v99
	s_waitcnt vmcnt(0)
	v_lshlrev_b32_e32 v12, 6, v100
	v_lshlrev_b32_e32 v13, 6, v101
	v_lshlrev_b32_e32 v14, 6, v102
	v_lshlrev_b32_e32 v15, 6, v103
	v_lshlrev_b32_e32 v16, 6, v104
	v_lshlrev_b32_e32 v17, 6, v105
	v_lshlrev_b32_e32 v18, 6, v106
	v_lshlrev_b32_e32 v19, 6, v107
	v_lshlrev_b32_e32 v20, 6, v108
	v_lshlrev_b32_e32 v21, 6, v109
	v_lshlrev_b32_e32 v22, 6, v110
	s_movk_i32 s8, 0x80
	s_movk_i32 s12, 0xff
	s_movk_i32 s14, 0x17f
	v_lshlrev_b32_e32 v2, 9, v96
	v_lshlrev_b32_e32 v3, 9, v97
	v_lshlrev_b32_e32 v23, 9, v98
	v_lshlrev_b32_e32 v24, 9, v99
	v_lshlrev_b32_e32 v25, 9, v100
	v_lshlrev_b32_e32 v26, 9, v101
	v_lshlrev_b32_e32 v27, 9, v102
	v_lshlrev_b32_e32 v28, 9, v103
	v_lshlrev_b32_e32 v29, 9, v104
	v_lshlrev_b32_e32 v30, 9, v105
	v_lshlrev_b32_e32 v31, 9, v106
	v_lshlrev_b32_e32 v32, 9, v107
	v_lshlrev_b32_e32 v33, 9, v108
	v_lshlrev_b32_e32 v34, 9, v109
	v_lshlrev_b32_e32 v35, 9, v110
	v_lshl_add_u32 v5, v5, 4, 0
	v_mul_u32_u24_e32 v4, 0x90, v4
	v_lshl_add_u64 v[86:87], v[0:1], 0, s[18:19]
	v_lshl_add_u64 v[0:1], s[16:17], 0, v[64:65]
	s_mov_b64 s[16:17], 0x2e88000
	v_cmp_gt_u32_e64 s[6:7], s6, v210
	v_lshrrev_b32_e32 v92, 2, v210
	s_mov_b32 s77, 0
	v_add_u32_e32 v93, 0, v6
	v_cmp_gt_u32_e64 s[8:9], s8, v210
	v_cmp_lt_u32_e64 s[10:11], s10, v210
	v_cmp_lt_u32_e64 s[12:13], s12, v210
	v_cmp_lt_u32_e64 s[14:15], s14, v210
	v_or_b32_e32 v71, 32, v70
	v_lshl_add_u64 v[88:89], v[0:1], 0, s[16:17]
	v_lshlrev_b32_e32 v90, 8, v116
	v_mov_b32_e32 v91, v65
	s_lshl_b32 s86, s2, 2
	s_lshl_b32 s87, s58, 2
	s_lshl_b32 s88, s2, 4
	s_lshl_b32 s89, s58, 4
	s_lshl_b32 s90, s2, 6
	s_lshl_b32 s91, s58, 6
	s_movk_i32 s92, 0x3000
	v_add_u32_e32 v117, 0, v7
	s_mov_b32 s93, 0xbfb8aa3b
	s_mov_b32 s94, 0x800000
	s_mov_b32 s95, 0x3f317217
	s_mov_b32 s96, 0x7f800000
	s_mov_b32 s97, 0x3d800000
	v_add_u32_e32 v118, 0, v8
	v_add_u32_e32 v119, 0, v9
	v_add_u32_e32 v120, 0, v10
	v_add_u32_e32 v121, 0, v11
	v_add_u32_e32 v122, 0, v12
	v_add_u32_e32 v123, 0, v13
	v_add_u32_e32 v124, 0, v14
	v_add_u32_e32 v125, 0, v15
	v_add_u32_e32 v126, 0, v16
	v_add_u32_e32 v127, 0, v17
	v_add_u32_e32 v128, 0, v18
	v_add_u32_e32 v129, 0, v19
	v_add_u32_e32 v130, 0, v20
	v_add_u32_e32 v131, 0, v21
	v_add_u32_e32 v132, 0, v22
	v_add_u32_e32 v133, v112, v2
	v_add_u32_e32 v134, v112, v3
	v_add_u32_e32 v135, v112, v23
	v_add_u32_e32 v136, v112, v24
	v_add_u32_e32 v137, v112, v25
	v_add_u32_e32 v138, v112, v26
	v_add_u32_e32 v139, v112, v27
	v_add_u32_e32 v140, v112, v28
	v_add_u32_e32 v141, v112, v29
	v_add_u32_e32 v142, v112, v30
	v_add_u32_e32 v143, v112, v31
	v_add_u32_e32 v144, v112, v32
	v_add_u32_e32 v145, v112, v33
	v_add_u32_e32 v146, v112, v34
	v_add_u32_e32 v147, v112, v35
	s_mov_b32 s84, 0x82000
	v_mov_b32_e32 v148, 0x41b17218
	v_add_u32_e32 v149, v5, v4
	s_mov_b32 s78, s2
	s_and_b32 s16, s2, 7
	s_lshr_b32 s17, s2, 3
	s_lshr_b32 s18, s16, 1
	s_lshl_b32 s18, s18, 8
	s_and_b32 s19, s16, 1
	s_lshl_b32 s19, s19, 5
	s_add_i32 s19, s19, s17
	s_or_b32 s18, s18, s19
	s_cmpk_eq_i32 s58, 0x100
	s_cselect_b32 s78, s18, s2
	s_lshl_b32 s86, s78, 2
	s_lshl_b32 s88, s78, 4
	s_lshl_b32 s90, s78, 6
	s_branch .LBB0_1962
; __device__ __forceinline__ unsigned cvt_pk_bf16(float lo, float hi) { unsigned r; asm volatile("v_cvt_pk_bf16_f32 %0, %1, %2" : "=v"(r) : "v"(lo), "v"(hi)); return r; }
; __device__ __forceinline__ void gla_g1(const Params& P, unsigned char* lds) {
;     ...
;     for (int it = blockIdx.x; it < NITEM; it += gridDim.x) {
;     ...
; #pragma unroll
;         for (int mt = 0; mt < 8; ++mt)
; #pragma unroll
;             for (int nt = 0; nt < 2; ++nt) { u32x2 w; w.x = cvt_pk_bf16(acc[mt][nt][0], acc[mt][nt][1]); w.y = cvt_pk_bf16(acc[mt][nt][2], acc[mt][nt][3]);
;                 *(u32x2*)(KVT + ((size_t)it * 256 + 32 * wid + 16 * nt + fr) * 128 + 16 * mt + 4 * fq) = w; }
;         __syncthreads();
.LBB0_1961:
	s_waitcnt vmcnt(0)
	s_ashr_i32 s79, s78, 31
	s_lshl_b64 s[16:17], s[78:79], 16
	v_cvt_pk_bf16_f32 v56, v56, v57
	v_cvt_pk_bf16_f32 v57, v58, v59
	v_lshl_add_u64 v[58:59], s[16:17], 0, v[90:91]
	v_lshl_add_u64 v[150:151], v[72:73], 0, v[58:59]
	v_or_b32_e32 v58, 0x1000, v58
	global_store_dwordx2 v[150:151], v[56:57], off
	v_cvt_pk_bf16_f32 v56, v60, v61
	v_lshl_add_u64 v[60:61], v[72:73], 0, v[58:59]
	v_cvt_pk_bf16_f32 v57, v62, v63
	global_store_dwordx2 v[60:61], v[56:57], off
	v_cvt_pk_bf16_f32 v48, v48, v49
	v_cvt_pk_bf16_f32 v49, v50, v51
	v_lshl_add_u64 v[50:51], v[74:75], 0, v[58:59]
	global_store_dwordx2 v[150:151], v[48:49], off offset:32
	v_cvt_pk_bf16_f32 v48, v52, v53
	v_cvt_pk_bf16_f32 v49, v54, v55
	global_store_dwordx2 v[50:51], v[48:49], off
	v_cvt_pk_bf16_f32 v40, v40, v41
	v_cvt_pk_bf16_f32 v41, v42, v43
	v_lshl_add_u64 v[42:43], v[76:77], 0, v[58:59]
	global_store_dwordx2 v[150:151], v[40:41], off offset:64
	v_cvt_pk_bf16_f32 v40, v44, v45
	v_cvt_pk_bf16_f32 v41, v46, v47
	global_store_dwordx2 v[42:43], v[40:41], off
	v_cvt_pk_bf16_f32 v32, v32, v33
	v_cvt_pk_bf16_f32 v33, v34, v35
	v_lshl_add_u64 v[34:35], v[78:79], 0, v[58:59]
	global_store_dwordx2 v[150:151], v[32:33], off offset:96
	v_cvt_pk_bf16_f32 v32, v36, v37
	v_cvt_pk_bf16_f32 v33, v38, v39
	global_store_dwordx2 v[34:35], v[32:33], off
	v_cvt_pk_bf16_f32 v24, v24, v25
	v_cvt_pk_bf16_f32 v25, v26, v27
	v_lshl_add_u64 v[26:27], v[80:81], 0, v[58:59]
	global_store_dwordx2 v[150:151], v[24:25], off offset:128
	v_cvt_pk_bf16_f32 v24, v28, v29
	v_cvt_pk_bf16_f32 v25, v30, v31
	global_store_dwordx2 v[26:27], v[24:25], off
	v_cvt_pk_bf16_f32 v16, v16, v17
	v_cvt_pk_bf16_f32 v17, v18, v19
	v_lshl_add_u64 v[18:19], v[82:83], 0, v[58:59]
	global_store_dwordx2 v[150:151], v[16:17], off offset:160
	v_cvt_pk_bf16_f32 v16, v20, v21
	v_cvt_pk_bf16_f32 v17, v22, v23
	global_store_dwordx2 v[18:19], v[16:17], off
	v_cvt_pk_bf16_f32 v8, v8, v9
	v_cvt_pk_bf16_f32 v9, v10, v11
	v_lshl_add_u64 v[10:11], v[84:85], 0, v[58:59]
	s_cmpk_lg_i32 s58, 0x100
	s_cbranch_scc1 .Lg1map_orig
	s_cmpk_gt_i32 s78, 0x3ff
	s_cbranch_scc1 .Lg1map_end
	s_add_i32 s79, s78, 64
	s_xor_b32 s80, s79, s78
	s_bitcmp1_b32 s80, 8
	s_cbranch_scc0 .Lg1map_set
	s_cmp_lt_u32 s2, 64
	s_cbranch_scc0 .Lg1map_end
	s_and_b32 s79, s2, 7
	s_lshl_b32 s79, s79, 3
	s_lshr_b32 s80, s2, 3
	s_and_b32 s81, s80, 1
	s_lshl_b32 s81, s81, 2
	s_lshr_b32 s80, s80, 1
	s_add_i32 s79, s79, s81
	s_add_i32 s79, s79, s80
	s_addk_i32 s79, 0x400
	s_branch .Lg1map_set
.Lg1map_end:
	s_movk_i32 s79, 0x7fff
	s_branch .Lg1map_set
.Lg1map_orig:
	s_add_i32 s79, s78, s58
.Lg1map_set:
	s_mov_b32 s78, s79
	s_lshl_b32 s86, s78, 2
	s_lshl_b32 s88, s78, 4
	s_lshl_b32 s90, s78, 6
	global_store_dwordx2 v[150:151], v[8:9], off offset:192
	v_cvt_pk_bf16_f32 v8, v12, v13
	v_cvt_pk_bf16_f32 v9, v14, v15
	global_store_dwordx2 v[10:11], v[8:9], off
	v_cvt_pk_bf16_f32 v0, v0, v1
	v_cvt_pk_bf16_f32 v1, v2, v3
	v_lshl_add_u64 v[2:3], v[86:87], 0, v[58:59]
	s_cmpk_lt_i32 s78, 0x440
	global_store_dwordx2 v[150:151], v[0:1], off offset:224
	v_cvt_pk_bf16_f32 v0, v4, v5
	v_cvt_pk_bf16_f32 v1, v6, v7
	global_store_dwordx2 v[2:3], v[0:1], off
	s_barrier
	s_cbranch_scc0 .LBB0_1978
